# FFN-in: adaLN shift vectors prefetched in first K iteration (register-staged into LDS), epilogue reads them from LDS instead of global
# speedup vs baseline: 1.0055x; 1.0046x over previous
.LBB0_556:
	v_mov_b64_e32 v[0:1], 0x420
	s_ashr_i32 s49, s48, 31
	v_cmp_lt_i64_e32 vcc, s[50:51], v[0:1]
	s_lshl_b64 s[50:51], s[48:49], 19
	s_add_u32 s50, s4, s50
	s_addc_u32 s51, s5, s51
	s_and_b64 s[52:53], vcc, exec
	s_cselect_b32 s49, s51, s59
	s_cselect_b32 s67, s50, s58
	s_ashr_i32 s47, s46, 31
	s_lshl_b64 s[52:53], s[46:47], 19
	s_add_u32 s52, s10, s52
	s_addc_u32 s53, s11, s53
	s_and_b64 s[62:63], vcc, exec
	s_cselect_b32 s47, s53, s61
	s_cselect_b32 s68, s52, s60
	s_add_u32 s58, s58, 0x40080
	s_addc_u32 s59, s59, 0
	s_add_u32 s69, s60, 0x100
	s_addc_u32 s70, s61, 0
	s_mov_b32 s71, -2
	v_add_u32_e32 v96, 0x10000, v193
	ds_read_b128 v[80:83], v96
	ds_read_b128 v[88:91], v96 offset:1024
	ds_read_b128 v[102:105], v96 offset:2048
	ds_read_b128 v[106:109], v96 offset:3072
	s_add_u32 s60, s58, 0xfffc0080
	s_addc_u32 s61, s59, -1
	s_add_i32 s72, 0, 0x10000
	v_add_u32_e32 v96, s72, v193
	s_cmp_eq_u32 s71, 12
	s_cselect_b32 s63, s49, s61
	s_cselect_b32 s62, s67, s60
	s_cselect_b32 s61, s47, s70
	s_cselect_b32 s60, s68, s69
	s_lshl_b32 s100, s54, 8
	s_lshr_b32 s101, s18, 5
	s_add_i32 s100, s100, s101
	v_add_u32_e32 v244, s100, v192
	v_lshlrev_b32_e32 v244, 6, v244
	v_mov_b32_e32 v245, 0
	v_lshl_add_u64 v[244:245], v[154:155], 0, v[244:245]
	global_load_dwordx4 v[248:251], v[244:245], off
	global_load_dwordx4 v[244:247], v[244:245], off offset:1024
	s_cmp_gt_u32 s18, 0x400
	s_cbranch_scc1 .Lmodpf_skip
	s_lshl_b32 s100, s54, 8
	s_cmpk_lt_u32 s100, 0x2000
	s_cselect_b32 s100, 1, 2
	s_cmp_eq_u32 s18, 0
	s_cselect_b32 s100, 0, s100
	s_mul_i32 s100, s100, 0x1d800
	s_lshl_b32 s101, s55, 10
	s_add_i32 s100, s100, s101
	s_add_u32 s100, s44, s100
	s_addc_u32 s101, s45, 0
	v_lshlrev_b32_e32 v0, 4, v205
	global_load_dwordx4 v[0:3], v0, s[100:101]
.Lmodpf_skip:
	s_add_i32 m0, s27, 0xc000
	ds_read_b128 v[160:163], v195
	ds_read_b128 v[164:167], v195 offset:1024
	ds_read_b128 v[168:171], v195 offset:2048
	ds_read_b128 v[172:175], v195 offset:3072
	ds_read_b128 v[182:185], v195 offset:4096
	ds_read_b128 v[186:189], v195 offset:5120
	ds_read_b128 v[196:199], v195 offset:6144
	ds_read_b128 v[200:203], v195 offset:7168
	global_load_lds_dwordx4 v156, s[58:59]
	s_add_i32 m0, s27, 0xe000
	s_nop 0
	global_load_lds_dwordx4 v158, s[58:59]
	s_setprio 1
	s_barrier
	s_waitcnt lgkmcnt(0)
	v_mfma_f32_16x16x32_bf16 v[142:145], v[80:83], v[160:163], 0
	v_mfma_f32_16x16x32_bf16 v[138:141], v[102:105], v[160:163], 0
	v_mfma_f32_16x16x32_bf16 v[126:129], v[80:83], v[168:171], 0
	v_mfma_f32_16x16x32_bf16 v[122:125], v[102:105], v[168:171], 0
	v_mfma_f32_16x16x32_bf16 v[110:113], v[80:83], v[182:185], 0
	v_mfma_f32_16x16x32_bf16 v[98:101], v[102:105], v[182:185], 0
	v_mfma_f32_16x16x32_bf16 v[76:79], v[80:83], v[196:199], 0
	v_mfma_f32_16x16x32_bf16 v[72:75], v[102:105], v[196:199], 0
	v_mfma_f32_16x16x32_bf16 v[142:145], v[88:91], v[164:167], v[142:145]
	v_mfma_f32_16x16x32_bf16 v[138:141], v[106:109], v[164:167], v[138:141]
	v_mfma_f32_16x16x32_bf16 v[126:129], v[88:91], v[172:175], v[126:129]
	v_mfma_f32_16x16x32_bf16 v[122:125], v[106:109], v[172:175], v[122:125]
	v_mfma_f32_16x16x32_bf16 v[110:113], v[88:91], v[186:189], v[110:113]
	v_mfma_f32_16x16x32_bf16 v[98:101], v[106:109], v[186:189], v[98:101]
	v_mfma_f32_16x16x32_bf16 v[76:79], v[88:91], v[200:203], v[76:79]
	v_mfma_f32_16x16x32_bf16 v[72:75], v[106:109], v[200:203], v[72:75]
	s_barrier
	s_setprio 0
	s_add_i32 s76, 0, 0x14000
	s_add_i32 s72, s72, s18
	v_add_u32_e32 v96, s76, v193
	v_lshl_add_u64 v[176:177], s[60:61], 0, v[150:151]
	s_mov_b32 m0, s72
	ds_read_b128 v[224:227], v96
	ds_read_b128 v[228:231], v96 offset:1024
	ds_read_b128 v[232:235], v96 offset:2048
	ds_read_b128 v[236:239], v96 offset:3072
	global_load_lds_dwordx4 v150, s[60:61]
	v_lshl_add_u64 v[190:191], s[60:61], 0, v[146:147]
	s_add_i32 m0, s72, 0x2000
	s_nop 0
	global_load_lds_dwordx4 v146, s[60:61]
	s_setprio 1
	s_barrier
	s_waitcnt lgkmcnt(0)
	v_mfma_f32_16x16x32_bf16 v[134:137], v[224:227], v[160:163], 0
	v_mfma_f32_16x16x32_bf16 v[130:133], v[232:235], v[160:163], 0
	v_mfma_f32_16x16x32_bf16 v[118:121], v[224:227], v[168:171], 0
	s_mov_b32 m0, s27
	v_mfma_f32_16x16x32_bf16 v[114:117], v[232:235], v[168:171], 0
	v_lshl_add_u64 v[240:241], s[62:63], 0, v[152:153]
	v_mfma_f32_16x16x32_bf16 v[92:95], v[224:227], v[182:185], 0
	v_mfma_f32_16x16x32_bf16 v[84:87], v[232:235], v[182:185], 0
	v_mfma_f32_16x16x32_bf16 v[68:71], v[224:227], v[196:199], 0
	v_mfma_f32_16x16x32_bf16 v[64:67], v[232:235], v[196:199], 0
	v_mfma_f32_16x16x32_bf16 v[134:137], v[228:231], v[164:167], v[134:137]
	v_mfma_f32_16x16x32_bf16 v[130:133], v[236:239], v[164:167], v[130:133]
	v_mfma_f32_16x16x32_bf16 v[118:121], v[228:231], v[172:175], v[118:121]
	v_mfma_f32_16x16x32_bf16 v[114:117], v[236:239], v[172:175], v[114:117]
	v_mfma_f32_16x16x32_bf16 v[92:95], v[228:231], v[186:189], v[92:95]
	v_mfma_f32_16x16x32_bf16 v[84:87], v[236:239], v[186:189], v[84:87]
	v_mfma_f32_16x16x32_bf16 v[68:71], v[228:231], v[200:203], v[68:71]
	v_mfma_f32_16x16x32_bf16 v[64:67], v[236:239], v[200:203], v[64:67]
	s_barrier
	s_setprio 0
	ds_read_b128 v[160:163], v195 offset:16384
	ds_read_b128 v[164:167], v195 offset:17408
	ds_read_b128 v[168:171], v195 offset:18432
	ds_read_b128 v[172:175], v195 offset:19456
	ds_read_b128 v[182:185], v195 offset:20480
	ds_read_b128 v[186:189], v195 offset:21504
	ds_read_b128 v[196:199], v195 offset:22528
	ds_read_b128 v[200:203], v195 offset:23552
	global_load_lds_dwordx4 v152, s[62:63]
	v_lshl_add_u64 v[242:243], s[62:63], 0, v[148:149]
	s_mov_b32 m0, s28
	s_nop 0
	global_load_lds_dwordx4 v148, s[62:63]
	s_waitcnt vmcnt(12)
	s_setprio 1
	s_barrier
	s_waitcnt lgkmcnt(0)
	v_mfma_f32_16x16x32_bf16 v[60:63], v[80:83], v[160:163], 0
	v_mfma_f32_16x16x32_bf16 v[56:59], v[102:105], v[160:163], 0
	v_mfma_f32_16x16x32_bf16 v[44:47], v[80:83], v[168:171], 0
	v_mfma_f32_16x16x32_bf16 v[40:43], v[102:105], v[168:171], 0
	v_mfma_f32_16x16x32_bf16 v[28:31], v[80:83], v[182:185], 0
	v_mfma_f32_16x16x32_bf16 v[24:27], v[102:105], v[182:185], 0
	v_mfma_f32_16x16x32_bf16 v[12:15], v[80:83], v[196:199], 0
	v_mfma_f32_16x16x32_bf16 v[8:11], v[102:105], v[196:199], 0
	v_mfma_f32_16x16x32_bf16 v[60:63], v[88:91], v[164:167], v[60:63]
	v_mfma_f32_16x16x32_bf16 v[56:59], v[106:109], v[164:167], v[56:59]
	v_mfma_f32_16x16x32_bf16 v[44:47], v[88:91], v[172:175], v[44:47]
	v_mfma_f32_16x16x32_bf16 v[40:43], v[106:109], v[172:175], v[40:43]
	v_mfma_f32_16x16x32_bf16 v[28:31], v[88:91], v[186:189], v[28:31]
	v_mfma_f32_16x16x32_bf16 v[24:27], v[106:109], v[186:189], v[24:27]
	v_mfma_f32_16x16x32_bf16 v[12:15], v[88:91], v[200:203], v[12:15]
	v_mfma_f32_16x16x32_bf16 v[8:11], v[106:109], v[200:203], v[8:11]
	s_barrier
	s_setprio 0
	v_add_u32_e32 v96, 0x18000, v193
	ds_read_b128 v[80:83], v96
	ds_read_b128 v[88:91], v96 offset:1024
	ds_read_b128 v[102:105], v96 offset:2048
	ds_read_b128 v[106:109], v96 offset:3072
	s_add_u32 s74, s60, 0x40000
	s_addc_u32 s75, s61, 0
	s_add_i32 s72, s76, s18
	s_mov_b32 m0, s72
	s_nop 0
	global_load_lds_dwordx4 v150, s[74:75]
	s_add_i32 m0, s72, 0x2000
	s_nop 0
	global_load_lds_dwordx4 v146, s[74:75]
	s_waitcnt vmcnt(6)
	s_setprio 1
	s_barrier
	v_mfma_f32_16x16x32_bf16 v[52:55], v[224:227], v[160:163], 0
	v_add_f32_e32 v248, v248, v249
	v_add_f32_e32 v250, v250, v251
	v_add_f32_e32 v248, v248, v250
	v_add_f32_e32 v244, v244, v245
	v_add_f32_e32 v246, v246, v247
	v_add_f32_e32 v244, v244, v246
	v_mov_b32_e32 v249, v248
	v_mov_b32_e32 v245, v244
	s_nop 1
	v_permlane16_swap_b32_e32 v248, v249
	v_permlane16_swap_b32_e32 v244, v245
	s_nop 1
	v_add_f32_e32 v248, v248, v249
	v_add_f32_e32 v244, v244, v245
	v_mov_b32_e32 v249, v248
	v_mov_b32_e32 v245, v244
	s_nop 1
	v_permlane32_swap_b32_e32 v248, v249
	v_permlane32_swap_b32_e32 v244, v245
	s_nop 1
	v_add_f32_e32 v248, v248, v249
	v_add_f32_e32 v244, v244, v245
	v_fmamk_f32 v248, v248, 0x3a800000, v207
	v_fmamk_f32 v244, v244, 0x3a800000, v207
	v_rsq_f32_e32 v248, v248
	v_rsq_f32_e32 v244, v244
	s_nop 1
	s_lshr_b32 s101, s18, 3
	s_add_i32 s101, s101, 0x20000
	v_lshl_add_u32 v250, v192, 2, s101
	ds_write_b32 v250, v248
	ds_write_b32 v250, v244 offset:64
	s_cmp_gt_u32 s18, 0x400
	s_cbranch_scc1 .Lmodpf_skip2
	s_cmp_eq_u32 s18, 0
	s_cselect_b32 s101, 0, 0x800
	s_add_i32 s101, s101, 0x20400
	v_lshl_add_u32 v251, v205, 4, s101
	ds_write_b128 v251, v[0:3]
.Lmodpf_skip2:
	v_mfma_f32_16x16x32_bf16 v[48:51], v[232:235], v[160:163], 0
	v_mfma_f32_16x16x32_bf16 v[36:39], v[224:227], v[168:171], 0
	s_add_i32 s72, 0, 0x18000
	v_mfma_f32_16x16x32_bf16 v[32:35], v[232:235], v[168:171], 0
	v_add_u32_e32 v96, s72, v193
	v_mfma_f32_16x16x32_bf16 v[20:23], v[224:227], v[182:185], 0
	v_mfma_f32_16x16x32_bf16 v[16:19], v[232:235], v[182:185], 0
	v_mfma_f32_16x16x32_bf16 v[4:7], v[224:227], v[196:199], 0
	v_mfma_f32_16x16x32_bf16 v[0:3], v[232:235], v[196:199], 0
	v_mfma_f32_16x16x32_bf16 v[52:55], v[228:231], v[164:167], v[52:55]
	v_mfma_f32_16x16x32_bf16 v[48:51], v[236:239], v[164:167], v[48:51]
	v_mfma_f32_16x16x32_bf16 v[36:39], v[228:231], v[172:175], v[36:39]
	v_mfma_f32_16x16x32_bf16 v[32:35], v[236:239], v[172:175], v[32:35]
	v_mfma_f32_16x16x32_bf16 v[20:23], v[228:231], v[186:189], v[20:23]
	v_mfma_f32_16x16x32_bf16 v[16:19], v[236:239], v[186:189], v[16:19]
	v_mfma_f32_16x16x32_bf16 v[4:7], v[228:231], v[200:203], v[4:7]
	v_mfma_f32_16x16x32_bf16 v[0:3], v[236:239], v[200:203], v[0:3]
	s_barrier
	s_setprio 0
	s_add_u32 s62, s62, 0x40000
	s_addc_u32 s63, s63, 0
	s_mov_b32 m0, s37
	ds_read_b128 v[160:163], v195 offset:32768
	ds_read_b128 v[164:167], v195 offset:33792
	ds_read_b128 v[168:171], v195 offset:34816
	ds_read_b128 v[172:175], v195 offset:35840
	ds_read_b128 v[182:185], v195 offset:36864
	ds_read_b128 v[186:189], v195 offset:37888
	ds_read_b128 v[196:199], v195 offset:38912
	ds_read_b128 v[200:203], v195 offset:39936
	global_load_lds_dwordx4 v152, s[62:63]
	s_mov_b32 m0, s56
	s_nop 0
	global_load_lds_dwordx4 v148, s[62:63]
	s_setprio 1
	s_barrier
	s_waitcnt lgkmcnt(0)
	v_mfma_f32_16x16x32_bf16 v[142:145], v[80:83], v[160:163], v[142:145]
	v_mfma_f32_16x16x32_bf16 v[138:141], v[102:105], v[160:163], v[138:141]
	v_mfma_f32_16x16x32_bf16 v[126:129], v[80:83], v[168:171], v[126:129]
	v_mfma_f32_16x16x32_bf16 v[122:125], v[102:105], v[168:171], v[122:125]
	v_mfma_f32_16x16x32_bf16 v[110:113], v[80:83], v[182:185], v[110:113]
	v_mfma_f32_16x16x32_bf16 v[98:101], v[102:105], v[182:185], v[98:101]
	v_mfma_f32_16x16x32_bf16 v[76:79], v[80:83], v[196:199], v[76:79]
	v_mfma_f32_16x16x32_bf16 v[72:75], v[102:105], v[196:199], v[72:75]
	v_mfma_f32_16x16x32_bf16 v[142:145], v[88:91], v[164:167], v[142:145]
	v_mfma_f32_16x16x32_bf16 v[138:141], v[106:109], v[164:167], v[138:141]
	v_mfma_f32_16x16x32_bf16 v[126:129], v[88:91], v[172:175], v[126:129]
	v_mfma_f32_16x16x32_bf16 v[122:125], v[106:109], v[172:175], v[122:125]
	v_mfma_f32_16x16x32_bf16 v[110:113], v[88:91], v[186:189], v[110:113]
	v_mfma_f32_16x16x32_bf16 v[98:101], v[106:109], v[186:189], v[98:101]
	v_mfma_f32_16x16x32_bf16 v[76:79], v[88:91], v[200:203], v[76:79]
	v_mfma_f32_16x16x32_bf16 v[72:75], v[106:109], v[200:203], v[72:75]
	s_barrier
	s_setprio 0
	s_add_i32 s62, 0, 0x1c000
	s_add_i32 s63, s72, s18
	v_add_u32_e32 v96, s62, v193
	v_lshl_add_u64 v[176:177], v[176:177], 0, s[6:7]
	s_mov_b32 m0, s63
	ds_read_b128 v[224:227], v96
	ds_read_b128 v[228:231], v96 offset:1024
	ds_read_b128 v[232:235], v96 offset:2048
	ds_read_b128 v[236:239], v96 offset:3072
	global_load_lds_dwordx4 v[176:177], off
	v_lshl_add_u64 v[176:177], v[190:191], 0, s[6:7]
	s_add_i32 m0, s63, 0x2000
	s_nop 0
	global_load_lds_dwordx4 v[176:177], off
	s_setprio 1
	s_barrier
	s_waitcnt lgkmcnt(0)
	v_mfma_f32_16x16x32_bf16 v[134:137], v[224:227], v[160:163], v[134:137]
	v_mfma_f32_16x16x32_bf16 v[130:133], v[232:235], v[160:163], v[130:133]
	v_mfma_f32_16x16x32_bf16 v[118:121], v[224:227], v[168:171], v[118:121]
	s_mov_b32 m0, s64
	v_mfma_f32_16x16x32_bf16 v[114:117], v[232:235], v[168:171], v[114:117]
	v_lshl_add_u64 v[176:177], v[240:241], 0, s[6:7]
	v_mfma_f32_16x16x32_bf16 v[92:95], v[224:227], v[182:185], v[92:95]
	v_mfma_f32_16x16x32_bf16 v[84:87], v[232:235], v[182:185], v[84:87]
	v_mfma_f32_16x16x32_bf16 v[68:71], v[224:227], v[196:199], v[68:71]
	v_mfma_f32_16x16x32_bf16 v[64:67], v[232:235], v[196:199], v[64:67]
	v_mfma_f32_16x16x32_bf16 v[134:137], v[228:231], v[164:167], v[134:137]
	v_mfma_f32_16x16x32_bf16 v[130:133], v[236:239], v[164:167], v[130:133]
	v_mfma_f32_16x16x32_bf16 v[118:121], v[228:231], v[172:175], v[118:121]
	v_mfma_f32_16x16x32_bf16 v[114:117], v[236:239], v[172:175], v[114:117]
	v_mfma_f32_16x16x32_bf16 v[92:95], v[228:231], v[186:189], v[92:95]
	v_mfma_f32_16x16x32_bf16 v[84:87], v[236:239], v[186:189], v[84:87]
	v_mfma_f32_16x16x32_bf16 v[68:71], v[228:231], v[200:203], v[68:71]
	v_mfma_f32_16x16x32_bf16 v[64:67], v[236:239], v[200:203], v[64:67]
	s_barrier
	s_setprio 0
	ds_read_b128 v[160:163], v195 offset:49152
	ds_read_b128 v[164:167], v195 offset:50176
	ds_read_b128 v[168:171], v195 offset:51200
	ds_read_b128 v[172:175], v195 offset:52224
	ds_read_b128 v[182:185], v195 offset:53248
	ds_read_b128 v[186:189], v195 offset:54272
	ds_read_b128 v[196:199], v195 offset:55296
	ds_read_b128 v[200:203], v195 offset:56320
	global_load_lds_dwordx4 v[176:177], off
	v_lshl_add_u64 v[176:177], v[242:243], 0, s[6:7]
	s_mov_b32 m0, s65
	s_nop 0
	global_load_lds_dwordx4 v[176:177], off
	s_waitcnt vmcnt(10)
	s_setprio 1
	s_barrier
	s_waitcnt lgkmcnt(0)
	v_mfma_f32_16x16x32_bf16 v[60:63], v[80:83], v[160:163], v[60:63]
	v_mfma_f32_16x16x32_bf16 v[56:59], v[102:105], v[160:163], v[56:59]
	v_mfma_f32_16x16x32_bf16 v[44:47], v[80:83], v[168:171], v[44:47]
	v_mfma_f32_16x16x32_bf16 v[40:43], v[102:105], v[168:171], v[40:43]
	v_mfma_f32_16x16x32_bf16 v[28:31], v[80:83], v[182:185], v[28:31]
	v_mfma_f32_16x16x32_bf16 v[24:27], v[102:105], v[182:185], v[24:27]
	v_mfma_f32_16x16x32_bf16 v[12:15], v[80:83], v[196:199], v[12:15]
	v_mfma_f32_16x16x32_bf16 v[8:11], v[102:105], v[196:199], v[8:11]
	v_mfma_f32_16x16x32_bf16 v[60:63], v[88:91], v[164:167], v[60:63]
	v_mfma_f32_16x16x32_bf16 v[56:59], v[106:109], v[164:167], v[56:59]
	v_mfma_f32_16x16x32_bf16 v[44:47], v[88:91], v[172:175], v[44:47]
	v_mfma_f32_16x16x32_bf16 v[40:43], v[106:109], v[172:175], v[40:43]
	v_mfma_f32_16x16x32_bf16 v[28:31], v[88:91], v[186:189], v[28:31]
	v_mfma_f32_16x16x32_bf16 v[24:27], v[106:109], v[186:189], v[24:27]
	v_mfma_f32_16x16x32_bf16 v[12:15], v[88:91], v[200:203], v[12:15]
	v_mfma_f32_16x16x32_bf16 v[8:11], v[106:109], v[200:203], v[8:11]
	s_barrier
	s_setprio 0
	v_add_u32_e32 v96, 0x10000, v193
	ds_read_b128 v[80:83], v96
	ds_read_b128 v[88:91], v96 offset:1024
	ds_read_b128 v[102:105], v96 offset:2048
	ds_read_b128 v[106:109], v96 offset:3072
	s_add_u32 s60, s60, 0x40080
	s_addc_u32 s61, s61, 0
	s_add_i32 s62, s62, s18
	s_mov_b32 m0, s62
	s_nop 0
	global_load_lds_dwordx4 v150, s[60:61]
	s_add_i32 m0, s62, 0x2000
	s_nop 0
	global_load_lds_dwordx4 v146, s[60:61]
	s_waitcnt vmcnt(6)
	s_setprio 1
	s_barrier
	v_mfma_f32_16x16x32_bf16 v[52:55], v[224:227], v[160:163], v[52:55]
	v_mfma_f32_16x16x32_bf16 v[48:51], v[232:235], v[160:163], v[48:51]
	v_mfma_f32_16x16x32_bf16 v[36:39], v[224:227], v[168:171], v[36:39]
	s_add_i32 s71, s71, 2
	v_mfma_f32_16x16x32_bf16 v[32:35], v[232:235], v[168:171], v[32:35]
	s_add_u32 s58, s58, 0x100
	v_mfma_f32_16x16x32_bf16 v[20:23], v[224:227], v[182:185], v[20:23]
	s_addc_u32 s59, s59, 0
	v_mfma_f32_16x16x32_bf16 v[16:19], v[232:235], v[182:185], v[16:19]
	s_add_u32 s69, s69, 0x100
	v_mfma_f32_16x16x32_bf16 v[4:7], v[224:227], v[196:199], v[4:7]
	s_addc_u32 s70, s70, 0
	v_mfma_f32_16x16x32_bf16 v[0:3], v[232:235], v[196:199], v[0:3]
	s_cmp_gt_u32 s71, 13
	v_mfma_f32_16x16x32_bf16 v[52:55], v[228:231], v[164:167], v[52:55]
	v_mfma_f32_16x16x32_bf16 v[48:51], v[236:239], v[164:167], v[48:51]
	v_mfma_f32_16x16x32_bf16 v[36:39], v[228:231], v[172:175], v[36:39]
	v_mfma_f32_16x16x32_bf16 v[32:35], v[236:239], v[172:175], v[32:35]
	v_mfma_f32_16x16x32_bf16 v[20:23], v[228:231], v[186:189], v[20:23]
	v_mfma_f32_16x16x32_bf16 v[16:19], v[236:239], v[186:189], v[16:19]
	v_mfma_f32_16x16x32_bf16 v[4:7], v[228:231], v[200:203], v[4:7]
	v_mfma_f32_16x16x32_bf16 v[0:3], v[236:239], v[200:203], v[0:3]
	s_barrier
	s_setprio 0
.LBB0_557:
	s_add_u32 s60, s58, 0xfffc0080
	s_addc_u32 s61, s59, -1
	s_add_i32 s72, 0, 0x10000
	v_add_u32_e32 v96, s72, v193
	s_cmp_eq_u32 s71, 12
	s_cselect_b32 s63, s49, s61
	s_cselect_b32 s62, s67, s60
	s_cselect_b32 s61, s47, s70
	s_cselect_b32 s60, s68, s69
	s_add_i32 m0, s27, 0xc000
	ds_read_b128 v[160:163], v195
	ds_read_b128 v[164:167], v195 offset:1024
	ds_read_b128 v[168:171], v195 offset:2048
	ds_read_b128 v[172:175], v195 offset:3072
	ds_read_b128 v[182:185], v195 offset:4096
	ds_read_b128 v[186:189], v195 offset:5120
	ds_read_b128 v[196:199], v195 offset:6144
	ds_read_b128 v[200:203], v195 offset:7168
	global_load_lds_dwordx4 v156, s[58:59]
	s_add_i32 m0, s27, 0xe000
	s_nop 0
	global_load_lds_dwordx4 v158, s[58:59]
	s_setprio 1
	s_barrier
	s_waitcnt lgkmcnt(0)
	v_mfma_f32_16x16x32_bf16 v[142:145], v[80:83], v[160:163], v[142:145]
	v_mfma_f32_16x16x32_bf16 v[138:141], v[102:105], v[160:163], v[138:141]
	v_mfma_f32_16x16x32_bf16 v[126:129], v[80:83], v[168:171], v[126:129]
	v_mfma_f32_16x16x32_bf16 v[122:125], v[102:105], v[168:171], v[122:125]
	v_mfma_f32_16x16x32_bf16 v[110:113], v[80:83], v[182:185], v[110:113]
	v_mfma_f32_16x16x32_bf16 v[98:101], v[102:105], v[182:185], v[98:101]
	v_mfma_f32_16x16x32_bf16 v[76:79], v[80:83], v[196:199], v[76:79]
	v_mfma_f32_16x16x32_bf16 v[72:75], v[102:105], v[196:199], v[72:75]
	v_mfma_f32_16x16x32_bf16 v[142:145], v[88:91], v[164:167], v[142:145]
	v_mfma_f32_16x16x32_bf16 v[138:141], v[106:109], v[164:167], v[138:141]
	v_mfma_f32_16x16x32_bf16 v[126:129], v[88:91], v[172:175], v[126:129]
	v_mfma_f32_16x16x32_bf16 v[122:125], v[106:109], v[172:175], v[122:125]
	v_mfma_f32_16x16x32_bf16 v[110:113], v[88:91], v[186:189], v[110:113]
	v_mfma_f32_16x16x32_bf16 v[98:101], v[106:109], v[186:189], v[98:101]
	v_mfma_f32_16x16x32_bf16 v[76:79], v[88:91], v[200:203], v[76:79]
	v_mfma_f32_16x16x32_bf16 v[72:75], v[106:109], v[200:203], v[72:75]
	s_barrier
	s_setprio 0
	s_add_i32 s76, 0, 0x14000
	s_add_i32 s72, s72, s18
	v_add_u32_e32 v96, s76, v193
	v_lshl_add_u64 v[176:177], s[60:61], 0, v[150:151]
	s_mov_b32 m0, s72
	ds_read_b128 v[224:227], v96
	ds_read_b128 v[228:231], v96 offset:1024
	ds_read_b128 v[232:235], v96 offset:2048
	ds_read_b128 v[236:239], v96 offset:3072
	global_load_lds_dwordx4 v150, s[60:61]
	v_lshl_add_u64 v[190:191], s[60:61], 0, v[146:147]
	s_add_i32 m0, s72, 0x2000
	s_nop 0
	global_load_lds_dwordx4 v146, s[60:61]
	s_setprio 1
	s_barrier
	s_waitcnt lgkmcnt(0)
	v_mfma_f32_16x16x32_bf16 v[134:137], v[224:227], v[160:163], v[134:137]
	v_mfma_f32_16x16x32_bf16 v[130:133], v[232:235], v[160:163], v[130:133]
	v_mfma_f32_16x16x32_bf16 v[118:121], v[224:227], v[168:171], v[118:121]
	s_mov_b32 m0, s27
	v_mfma_f32_16x16x32_bf16 v[114:117], v[232:235], v[168:171], v[114:117]
	v_lshl_add_u64 v[240:241], s[62:63], 0, v[152:153]
	v_mfma_f32_16x16x32_bf16 v[92:95], v[224:227], v[182:185], v[92:95]
	v_mfma_f32_16x16x32_bf16 v[84:87], v[232:235], v[182:185], v[84:87]
	v_mfma_f32_16x16x32_bf16 v[68:71], v[224:227], v[196:199], v[68:71]
	v_mfma_f32_16x16x32_bf16 v[64:67], v[232:235], v[196:199], v[64:67]
	v_mfma_f32_16x16x32_bf16 v[134:137], v[228:231], v[164:167], v[134:137]
	v_mfma_f32_16x16x32_bf16 v[130:133], v[236:239], v[164:167], v[130:133]
	v_mfma_f32_16x16x32_bf16 v[118:121], v[228:231], v[172:175], v[118:121]
	v_mfma_f32_16x16x32_bf16 v[114:117], v[236:239], v[172:175], v[114:117]
	v_mfma_f32_16x16x32_bf16 v[92:95], v[228:231], v[186:189], v[92:95]
	v_mfma_f32_16x16x32_bf16 v[84:87], v[236:239], v[186:189], v[84:87]
	v_mfma_f32_16x16x32_bf16 v[68:71], v[228:231], v[200:203], v[68:71]
	v_mfma_f32_16x16x32_bf16 v[64:67], v[236:239], v[200:203], v[64:67]
	s_barrier
	s_setprio 0
	ds_read_b128 v[160:163], v195 offset:16384
	ds_read_b128 v[164:167], v195 offset:17408
	ds_read_b128 v[168:171], v195 offset:18432
	ds_read_b128 v[172:175], v195 offset:19456
	ds_read_b128 v[182:185], v195 offset:20480
	ds_read_b128 v[186:189], v195 offset:21504
	ds_read_b128 v[196:199], v195 offset:22528
	ds_read_b128 v[200:203], v195 offset:23552
	global_load_lds_dwordx4 v152, s[62:63]
	v_lshl_add_u64 v[242:243], s[62:63], 0, v[148:149]
	s_mov_b32 m0, s28
	s_nop 0
	global_load_lds_dwordx4 v148, s[62:63]
	s_waitcnt vmcnt(10)
	s_setprio 1
	s_barrier
	s_waitcnt lgkmcnt(0)
	v_mfma_f32_16x16x32_bf16 v[60:63], v[80:83], v[160:163], v[60:63]
	v_mfma_f32_16x16x32_bf16 v[56:59], v[102:105], v[160:163], v[56:59]
	v_mfma_f32_16x16x32_bf16 v[44:47], v[80:83], v[168:171], v[44:47]
	v_mfma_f32_16x16x32_bf16 v[40:43], v[102:105], v[168:171], v[40:43]
	v_mfma_f32_16x16x32_bf16 v[28:31], v[80:83], v[182:185], v[28:31]
	v_mfma_f32_16x16x32_bf16 v[24:27], v[102:105], v[182:185], v[24:27]
	v_mfma_f32_16x16x32_bf16 v[12:15], v[80:83], v[196:199], v[12:15]
	v_mfma_f32_16x16x32_bf16 v[8:11], v[102:105], v[196:199], v[8:11]
	v_mfma_f32_16x16x32_bf16 v[60:63], v[88:91], v[164:167], v[60:63]
	v_mfma_f32_16x16x32_bf16 v[56:59], v[106:109], v[164:167], v[56:59]
	v_mfma_f32_16x16x32_bf16 v[44:47], v[88:91], v[172:175], v[44:47]
	v_mfma_f32_16x16x32_bf16 v[40:43], v[106:109], v[172:175], v[40:43]
	v_mfma_f32_16x16x32_bf16 v[28:31], v[88:91], v[186:189], v[28:31]
	v_mfma_f32_16x16x32_bf16 v[24:27], v[106:109], v[186:189], v[24:27]
	v_mfma_f32_16x16x32_bf16 v[12:15], v[88:91], v[200:203], v[12:15]
	v_mfma_f32_16x16x32_bf16 v[8:11], v[106:109], v[200:203], v[8:11]
	s_barrier
	s_setprio 0
	v_add_u32_e32 v96, 0x18000, v193
	ds_read_b128 v[80:83], v96
	ds_read_b128 v[88:91], v96 offset:1024
	ds_read_b128 v[102:105], v96 offset:2048
	ds_read_b128 v[106:109], v96 offset:3072
	s_add_u32 s74, s60, 0x40000
	s_addc_u32 s75, s61, 0
	s_add_i32 s72, s76, s18
	s_mov_b32 m0, s72
	s_nop 0
	global_load_lds_dwordx4 v150, s[74:75]
	s_add_i32 m0, s72, 0x2000
	s_nop 0
	global_load_lds_dwordx4 v146, s[74:75]
	s_waitcnt vmcnt(6)
	s_setprio 1
	s_barrier
	v_mfma_f32_16x16x32_bf16 v[52:55], v[224:227], v[160:163], v[52:55]
	v_mfma_f32_16x16x32_bf16 v[48:51], v[232:235], v[160:163], v[48:51]
	v_mfma_f32_16x16x32_bf16 v[36:39], v[224:227], v[168:171], v[36:39]
	s_add_i32 s72, 0, 0x18000
	v_mfma_f32_16x16x32_bf16 v[32:35], v[232:235], v[168:171], v[32:35]
	v_add_u32_e32 v96, s72, v193
	v_mfma_f32_16x16x32_bf16 v[20:23], v[224:227], v[182:185], v[20:23]
	v_mfma_f32_16x16x32_bf16 v[16:19], v[232:235], v[182:185], v[16:19]
	v_mfma_f32_16x16x32_bf16 v[4:7], v[224:227], v[196:199], v[4:7]
	v_mfma_f32_16x16x32_bf16 v[0:3], v[232:235], v[196:199], v[0:3]
	v_mfma_f32_16x16x32_bf16 v[52:55], v[228:231], v[164:167], v[52:55]
	v_mfma_f32_16x16x32_bf16 v[48:51], v[236:239], v[164:167], v[48:51]
	v_mfma_f32_16x16x32_bf16 v[36:39], v[228:231], v[172:175], v[36:39]
	v_mfma_f32_16x16x32_bf16 v[32:35], v[236:239], v[172:175], v[32:35]
	v_mfma_f32_16x16x32_bf16 v[20:23], v[228:231], v[186:189], v[20:23]
	v_mfma_f32_16x16x32_bf16 v[16:19], v[236:239], v[186:189], v[16:19]
	v_mfma_f32_16x16x32_bf16 v[4:7], v[228:231], v[200:203], v[4:7]
	v_mfma_f32_16x16x32_bf16 v[0:3], v[236:239], v[200:203], v[0:3]
	s_barrier
	s_setprio 0
	s_add_u32 s62, s62, 0x40000
	s_addc_u32 s63, s63, 0
	s_mov_b32 m0, s37
	ds_read_b128 v[160:163], v195 offset:32768
	ds_read_b128 v[164:167], v195 offset:33792
	ds_read_b128 v[168:171], v195 offset:34816
	ds_read_b128 v[172:175], v195 offset:35840
	ds_read_b128 v[182:185], v195 offset:36864
	ds_read_b128 v[186:189], v195 offset:37888
	ds_read_b128 v[196:199], v195 offset:38912
	ds_read_b128 v[200:203], v195 offset:39936
	global_load_lds_dwordx4 v152, s[62:63]
	s_mov_b32 m0, s56
	s_nop 0
	global_load_lds_dwordx4 v148, s[62:63]
	s_setprio 1
	s_barrier
	s_waitcnt lgkmcnt(0)
	v_mfma_f32_16x16x32_bf16 v[142:145], v[80:83], v[160:163], v[142:145]
	v_mfma_f32_16x16x32_bf16 v[138:141], v[102:105], v[160:163], v[138:141]
	v_mfma_f32_16x16x32_bf16 v[126:129], v[80:83], v[168:171], v[126:129]
	v_mfma_f32_16x16x32_bf16 v[122:125], v[102:105], v[168:171], v[122:125]
	v_mfma_f32_16x16x32_bf16 v[110:113], v[80:83], v[182:185], v[110:113]
	v_mfma_f32_16x16x32_bf16 v[98:101], v[102:105], v[182:185], v[98:101]
	v_mfma_f32_16x16x32_bf16 v[76:79], v[80:83], v[196:199], v[76:79]
	v_mfma_f32_16x16x32_bf16 v[72:75], v[102:105], v[196:199], v[72:75]
	v_mfma_f32_16x16x32_bf16 v[142:145], v[88:91], v[164:167], v[142:145]
	v_mfma_f32_16x16x32_bf16 v[138:141], v[106:109], v[164:167], v[138:141]
	v_mfma_f32_16x16x32_bf16 v[126:129], v[88:91], v[172:175], v[126:129]
	v_mfma_f32_16x16x32_bf16 v[122:125], v[106:109], v[172:175], v[122:125]
	v_mfma_f32_16x16x32_bf16 v[110:113], v[88:91], v[186:189], v[110:113]
	v_mfma_f32_16x16x32_bf16 v[98:101], v[106:109], v[186:189], v[98:101]
	v_mfma_f32_16x16x32_bf16 v[76:79], v[88:91], v[200:203], v[76:79]
	v_mfma_f32_16x16x32_bf16 v[72:75], v[106:109], v[200:203], v[72:75]
	s_barrier
	s_setprio 0
	s_add_i32 s62, 0, 0x1c000
	s_add_i32 s63, s72, s18
	v_add_u32_e32 v96, s62, v193
	v_lshl_add_u64 v[176:177], v[176:177], 0, s[6:7]
	s_mov_b32 m0, s63
	ds_read_b128 v[224:227], v96
	ds_read_b128 v[228:231], v96 offset:1024
	ds_read_b128 v[232:235], v96 offset:2048
	ds_read_b128 v[236:239], v96 offset:3072
	global_load_lds_dwordx4 v[176:177], off
	v_lshl_add_u64 v[176:177], v[190:191], 0, s[6:7]
	s_add_i32 m0, s63, 0x2000
	s_nop 0
	global_load_lds_dwordx4 v[176:177], off
	s_setprio 1
	s_barrier
	s_waitcnt lgkmcnt(0)
	v_mfma_f32_16x16x32_bf16 v[134:137], v[224:227], v[160:163], v[134:137]
	v_mfma_f32_16x16x32_bf16 v[130:133], v[232:235], v[160:163], v[130:133]
	v_mfma_f32_16x16x32_bf16 v[118:121], v[224:227], v[168:171], v[118:121]
	s_mov_b32 m0, s64
	v_mfma_f32_16x16x32_bf16 v[114:117], v[232:235], v[168:171], v[114:117]
	v_lshl_add_u64 v[176:177], v[240:241], 0, s[6:7]
	v_mfma_f32_16x16x32_bf16 v[92:95], v[224:227], v[182:185], v[92:95]
	v_mfma_f32_16x16x32_bf16 v[84:87], v[232:235], v[182:185], v[84:87]
	v_mfma_f32_16x16x32_bf16 v[68:71], v[224:227], v[196:199], v[68:71]
	v_mfma_f32_16x16x32_bf16 v[64:67], v[232:235], v[196:199], v[64:67]
	v_mfma_f32_16x16x32_bf16 v[134:137], v[228:231], v[164:167], v[134:137]
	v_mfma_f32_16x16x32_bf16 v[130:133], v[236:239], v[164:167], v[130:133]
	v_mfma_f32_16x16x32_bf16 v[118:121], v[228:231], v[172:175], v[118:121]
	v_mfma_f32_16x16x32_bf16 v[114:117], v[236:239], v[172:175], v[114:117]
	v_mfma_f32_16x16x32_bf16 v[92:95], v[228:231], v[186:189], v[92:95]
	v_mfma_f32_16x16x32_bf16 v[84:87], v[236:239], v[186:189], v[84:87]
	v_mfma_f32_16x16x32_bf16 v[68:71], v[228:231], v[200:203], v[68:71]
	v_mfma_f32_16x16x32_bf16 v[64:67], v[236:239], v[200:203], v[64:67]
	s_barrier
	s_setprio 0
	ds_read_b128 v[160:163], v195 offset:49152
	ds_read_b128 v[164:167], v195 offset:50176
	ds_read_b128 v[168:171], v195 offset:51200
	ds_read_b128 v[172:175], v195 offset:52224
	ds_read_b128 v[182:185], v195 offset:53248
	ds_read_b128 v[186:189], v195 offset:54272
	ds_read_b128 v[196:199], v195 offset:55296
	ds_read_b128 v[200:203], v195 offset:56320
	global_load_lds_dwordx4 v[176:177], off
	v_lshl_add_u64 v[176:177], v[242:243], 0, s[6:7]
	s_mov_b32 m0, s65
	s_nop 0
	global_load_lds_dwordx4 v[176:177], off
	s_waitcnt vmcnt(10)
	s_setprio 1
	s_barrier
	s_waitcnt lgkmcnt(0)
	v_mfma_f32_16x16x32_bf16 v[60:63], v[80:83], v[160:163], v[60:63]
	v_mfma_f32_16x16x32_bf16 v[56:59], v[102:105], v[160:163], v[56:59]
	v_mfma_f32_16x16x32_bf16 v[44:47], v[80:83], v[168:171], v[44:47]
	v_mfma_f32_16x16x32_bf16 v[40:43], v[102:105], v[168:171], v[40:43]
	v_mfma_f32_16x16x32_bf16 v[28:31], v[80:83], v[182:185], v[28:31]
	v_mfma_f32_16x16x32_bf16 v[24:27], v[102:105], v[182:185], v[24:27]
	v_mfma_f32_16x16x32_bf16 v[12:15], v[80:83], v[196:199], v[12:15]
	v_mfma_f32_16x16x32_bf16 v[8:11], v[102:105], v[196:199], v[8:11]
	v_mfma_f32_16x16x32_bf16 v[60:63], v[88:91], v[164:167], v[60:63]
	v_mfma_f32_16x16x32_bf16 v[56:59], v[106:109], v[164:167], v[56:59]
	v_mfma_f32_16x16x32_bf16 v[44:47], v[88:91], v[172:175], v[44:47]
	v_mfma_f32_16x16x32_bf16 v[40:43], v[106:109], v[172:175], v[40:43]
	v_mfma_f32_16x16x32_bf16 v[28:31], v[88:91], v[186:189], v[28:31]
	v_mfma_f32_16x16x32_bf16 v[24:27], v[106:109], v[186:189], v[24:27]
	v_mfma_f32_16x16x32_bf16 v[12:15], v[88:91], v[200:203], v[12:15]
	v_mfma_f32_16x16x32_bf16 v[8:11], v[106:109], v[200:203], v[8:11]
	s_barrier
	s_setprio 0
	v_add_u32_e32 v96, 0x10000, v193
	ds_read_b128 v[80:83], v96
	ds_read_b128 v[88:91], v96 offset:1024
	ds_read_b128 v[102:105], v96 offset:2048
	ds_read_b128 v[106:109], v96 offset:3072
	s_add_u32 s60, s60, 0x40080
	s_addc_u32 s61, s61, 0
	s_add_i32 s62, s62, s18
	s_mov_b32 m0, s62
	s_nop 0
	global_load_lds_dwordx4 v150, s[60:61]
	s_add_i32 m0, s62, 0x2000
	s_nop 0
	global_load_lds_dwordx4 v146, s[60:61]
	s_waitcnt vmcnt(6)
	s_setprio 1
	s_barrier
	v_mfma_f32_16x16x32_bf16 v[52:55], v[224:227], v[160:163], v[52:55]
	v_mfma_f32_16x16x32_bf16 v[48:51], v[232:235], v[160:163], v[48:51]
	v_mfma_f32_16x16x32_bf16 v[36:39], v[224:227], v[168:171], v[36:39]
	s_add_i32 s71, s71, 2
	v_mfma_f32_16x16x32_bf16 v[32:35], v[232:235], v[168:171], v[32:35]
	s_add_u32 s58, s58, 0x100
	v_mfma_f32_16x16x32_bf16 v[20:23], v[224:227], v[182:185], v[20:23]
	s_addc_u32 s59, s59, 0
	v_mfma_f32_16x16x32_bf16 v[16:19], v[232:235], v[182:185], v[16:19]
	s_add_u32 s69, s69, 0x100
	v_mfma_f32_16x16x32_bf16 v[4:7], v[224:227], v[196:199], v[4:7]
	s_addc_u32 s70, s70, 0
	v_mfma_f32_16x16x32_bf16 v[0:3], v[232:235], v[196:199], v[0:3]
	s_cmp_gt_u32 s71, 13
	v_mfma_f32_16x16x32_bf16 v[52:55], v[228:231], v[164:167], v[52:55]
	v_mfma_f32_16x16x32_bf16 v[48:51], v[236:239], v[164:167], v[48:51]
	v_mfma_f32_16x16x32_bf16 v[36:39], v[228:231], v[172:175], v[36:39]
	v_mfma_f32_16x16x32_bf16 v[32:35], v[236:239], v[172:175], v[32:35]
	v_mfma_f32_16x16x32_bf16 v[20:23], v[228:231], v[186:189], v[20:23]
	v_mfma_f32_16x16x32_bf16 v[16:19], v[236:239], v[186:189], v[16:19]
	v_mfma_f32_16x16x32_bf16 v[4:7], v[228:231], v[200:203], v[4:7]
	v_mfma_f32_16x16x32_bf16 v[0:3], v[236:239], v[200:203], v[0:3]
	s_barrier
	s_setprio 0
	s_cbranch_scc0 .LBB0_557
	s_waitcnt lgkmcnt(0)
	s_lshl_b32 s47, s54, 8
	s_add_i32 s47, s47, s57
	v_or_b32_e32 v162, s47, v192
	s_lshl_b32 s100, s57, 2
	s_add_i32 s100, s100, 0x20000
	v_lshl_add_u32 v244, v192, 2, s100
	ds_read_b32 v245, v244 offset:64
	ds_read_b32 v246, v244 offset:128
	ds_read_b32 v247, v244 offset:192
	ds_read_b32 v248, v244 offset:512
	ds_read_b32 v249, v244 offset:576
	ds_read_b32 v250, v244 offset:640
	ds_read_b32 v251, v244 offset:704
	ds_read_b32 v244, v244
	v_or_b32_e32 v190, 16, v162
	v_or_b32_e32 v188, 32, v162
	v_or_b32_e32 v186, 48, v162
	v_add_u32_e32 v184, 0x80, v162
	v_add_u32_e32 v172, 0x90, v162
	v_add_u32_e32 v168, 0xa0, v162
	v_add_u32_e32 v164, 0xb0, v162
	s_cmpk_lt_u32 s47, 0x2000
	s_cselect_b32 s47, 1, 2
	v_mov_b32_e32 v218, s47
	v_cmp_lt_i32_e32 vcc, s23, v162
	v_lshl_or_b32 v166, s55, 8, v194
	v_ashrrev_i32_e32 v167, 31, v166
	v_cndmask_b32_e32 v185, 0, v218, vcc
	v_mov_b32_e32 v96, 0x20400
	v_mov_b32_e32 v82, 0x20c00
	v_cndmask_b32_e32 v96, v96, v82, vcc
	v_lshl_add_u32 v96, v194, 2, v96
	ds_read_b128 v[80:83], v96 offset:16
	ds_read_b128 v[88:91], v96
	ds_read_b128 v[102:105], v96 offset:528
	ds_read_b128 v[106:109], v96 offset:512
	v_lshl_or_b32 v160, s55, 7, v194
	v_cmp_lt_i32_e32 vcc, s23, v190
	s_waitcnt vmcnt(0)
	s_waitcnt lgkmcnt(0)
	v_mov_b32_e32 v96, v244
	v_mov_b64_e32 v[170:171], s[42:43]
	v_ashrrev_i32_e32 v161, 31, v160
	v_mad_i64_i32 v[170:171], s[54:55], v162, s31, v[170:171]
	v_lshl_add_u64 v[224:225], v[160:161], 1, v[170:171]
	v_pk_mul_f32 v[182:183], v[82:83], s[0:1] op_sel_hi:[1,0]
	v_pk_mul_f32 v[176:177], v[80:81], s[0:1] op_sel_hi:[1,0]
	v_pk_mul_f32 v[174:175], v[90:91], s[0:1] op_sel_hi:[1,0]
	v_pk_mul_f32 v[170:171], v[88:89], s[0:1] op_sel_hi:[1,0]
	v_mul_f32_e32 v226, 0xbfb8aa3b, v96
	v_pk_fma_f32 v[228:229], v[144:145], v[226:227], v[174:175] op_sel_hi:[1,0,1]
	v_pk_fma_f32 v[230:231], v[142:143], v[226:227], v[170:171] op_sel_hi:[1,0,1]
	v_pk_fma_f32 v[232:233], v[140:141], v[226:227], v[182:183] op_sel_hi:[1,0,1]
	v_pk_fma_f32 v[226:227], v[138:139], v[226:227], v[176:177] op_sel_hi:[1,0,1]
	v_exp_f32_e32 v230, v230
	v_exp_f32_e32 v226, v226
	v_exp_f32_e32 v231, v231
	v_exp_f32_e32 v227, v227
	v_exp_f32_e32 v232, v232
	v_exp_f32_e32 v233, v233
	v_exp_f32_e32 v228, v228
	v_exp_f32_e32 v229, v229
	v_pk_add_f32 v[230:231], v[230:231], 1.0 op_sel_hi:[1,0]
	v_pk_add_f32 v[232:233], v[232:233], 1.0 op_sel_hi:[1,0]
	v_pk_add_f32 v[226:227], v[226:227], 1.0 op_sel_hi:[1,0]
	v_pk_add_f32 v[228:229], v[228:229], 1.0 op_sel_hi:[1,0]
	v_rcp_f32_e32 v230, v230
	v_rcp_f32_e32 v226, v226
	v_rcp_f32_e32 v231, v231
	v_rcp_f32_e32 v227, v227
	v_rcp_f32_e32 v232, v232
	v_rcp_f32_e32 v233, v233
	v_rcp_f32_e32 v228, v228
	v_rcp_f32_e32 v229, v229
	v_pk_fma_f32 v[142:143], v[142:143], v[96:97], v[88:89] op_sel_hi:[1,0,1]
	v_pk_fma_f32 v[140:141], v[140:141], v[96:97], v[82:83] op_sel_hi:[1,0,1]
	v_pk_fma_f32 v[138:139], v[138:139], v[96:97], v[80:81] op_sel_hi:[1,0,1]
	v_pk_fma_f32 v[134:135], v[134:135], v[96:97], v[106:107] op_sel_hi:[1,0,1]
	v_pk_fma_f32 v[132:133], v[132:133], v[96:97], v[104:105] op_sel_hi:[1,0,1]
	v_pk_fma_f32 v[130:131], v[130:131], v[96:97], v[102:103] op_sel_hi:[1,0,1]
	v_pk_fma_f32 v[144:145], v[144:145], v[96:97], v[90:91] op_sel_hi:[1,0,1]
	v_pk_fma_f32 v[136:137], v[136:137], v[96:97], v[108:109] op_sel_hi:[1,0,1]
	v_pk_mul_f32 v[134:135], v[142:143], v[134:135]
	v_pk_mul_f32 v[132:133], v[140:141], v[132:133]
	v_pk_mul_f32 v[130:131], v[138:139], v[130:131]
	v_pk_mul_f32 v[136:137], v[144:145], v[136:137]
	v_pk_mul_f32 v[134:135], v[134:135], v[230:231]
	v_pk_mul_f32 v[138:139], v[132:133], v[232:233]
	v_pk_mul_f32 v[132:133], v[130:131], v[226:227]
	v_cvt_pk_bf16_f32 v130, v134, v135
	v_pk_mul_f32 v[136:137], v[136:137], v[228:229]
	v_cvt_pk_bf16_f32 v131, v136, v137
	v_cvt_pk_bf16_f32 v132, v132, v133
	v_cvt_pk_bf16_f32 v133, v138, v139
	global_store_dwordx4 v[224:225], v[130:133], off
	s_nop 0
	v_cndmask_b32_e32 v130, 0, v218, vcc
	v_cmp_ne_u32_e32 vcc, v130, v185
	s_and_saveexec_b64 s[54:55], vcc
	s_cbranch_execz .LBB0_560
	v_mul_u32_u24_e32 v80, 0x7600, v130
	v_lshlrev_b32_e32 v96, 2, v80
	v_lshl_add_u64 v[80:81], s[44:45], 0, v[96:97]
	v_lshl_add_u64 v[106:107], v[166:167], 2, v[80:81]
	global_load_dwordx4 v[88:91], v[106:107], off
	global_load_dwordx4 v[80:83], v[106:107], off offset:16
	global_load_dwordx4 v[102:105], v[106:107], off offset:528
	s_nop 0
	global_load_dwordx4 v[106:109], v[106:107], off offset:512
	v_mov_b32_e32 v185, v130
	s_waitcnt vmcnt(0)
	v_pk_mul_f32 v[170:171], v[88:89], s[0:1] op_sel_hi:[1,0]
	v_pk_mul_f32 v[174:175], v[90:91], s[0:1] op_sel_hi:[1,0]
	v_pk_mul_f32 v[176:177], v[80:81], s[0:1] op_sel_hi:[1,0]
	v_pk_mul_f32 v[182:183], v[82:83], s[0:1] op_sel_hi:[1,0]
